# attention-norm phase context rows: split-K partial fold loads of all four column groups issued together (were 8 serialized round trips per wave)
# speedup vs baseline: 1.0136x; 1.0074x over previous
.LBB0_434:
	s_or_b64 exec, exec, s[2:3]
	v_cmp_lt_i32_e32 vcc, s28, v32
	s_and_b64 s[4:5], s[12:13], vcc
	s_and_saveexec_b64 s[2:3], s[4:5]
	s_cbranch_execz .LBB0_436
	v_lshlrev_b64 v[62:63], 11, v[184:185]
	v_lshl_add_u64 v[64:65], v[44:45], 0, v[62:63]
	v_add_co_u32_e32 v66, vcc, 0x800000, v64
	global_load_dwordx2 v[70:71], v[64:65], off
	s_nop 0
	v_addc_co_u32_e32 v67, vcc, 0, v65, vcc
	global_load_dwordx2 v[82:83], v[66:67], off
	v_add_co_u32_e32 v68, vcc, 0x1000000, v64
	v_lshlrev_b64 v[62:63], 12, v[184:185]
	s_nop 0
	v_addc_co_u32_e32 v69, vcc, 0, v65, vcc
	global_load_dwordx2 v[84:85], v[68:69], off
	global_load_dwordx4 v[78:81], v[34:35], off
	global_load_dwordx2 v[100:101], v[64:65], off offset:512
	global_load_dwordx2 v[102:103], v[66:67], off offset:512
	global_load_dwordx2 v[104:105], v[68:69], off offset:512
	global_load_dwordx4 v[106:109], v[36:37], off
	global_load_dwordx2 v[110:111], v[64:65], off offset:1024
	global_load_dwordx2 v[112:113], v[66:67], off offset:1024
	global_load_dwordx2 v[114:115], v[68:69], off offset:1024
	global_load_dwordx4 v[116:119], v[38:39], off
	global_load_dwordx2 v[120:121], v[64:65], off offset:1536
	global_load_dwordx2 v[122:123], v[66:67], off offset:1536
	global_load_dwordx2 v[124:125], v[68:69], off offset:1536
	global_load_dwordx4 v[126:129], v[40:41], off
	v_lshl_add_u64 v[62:63], v[46:47], 0, v[62:63]
	s_waitcnt vmcnt(0)
	v_lshlrev_b32_e32 v86, 16, v70
	v_and_b32_e32 v87, 0xffff0000, v70
	v_lshlrev_b32_e32 v70, 16, v71
	v_and_b32_e32 v71, 0xffff0000, v71
	v_pk_add_f32 v[86:87], v[86:87], 0 op_sel_hi:[1,0]
	v_pk_add_f32 v[70:71], v[70:71], 0 op_sel_hi:[1,0]
	v_lshlrev_b32_e32 v88, 16, v82
	v_and_b32_e32 v89, 0xffff0000, v82
	v_lshlrev_b32_e32 v82, 16, v83
	v_and_b32_e32 v83, 0xffff0000, v83
	v_pk_add_f32 v[86:87], v[86:87], v[88:89]
	v_lshlrev_b32_e32 v88, 16, v84
	v_and_b32_e32 v89, 0xffff0000, v84
	v_pk_add_f32 v[70:71], v[70:71], v[82:83]
	v_lshlrev_b32_e32 v82, 16, v85
	v_and_b32_e32 v83, 0xffff0000, v85
	v_pk_add_f32 v[84:85], v[86:87], v[88:89]
	v_pk_add_f32 v[70:71], v[70:71], v[82:83]
	v_pk_fma_f32 v[28:29], v[78:79], v[84:85], v[28:29]
	v_pk_fma_f32 v[30:31], v[80:81], v[70:71], v[30:31]
	global_store_dwordx4 v[62:63], v[28:31], off
	v_mov_b64_e32 v[70:71], v[100:101]
	v_mov_b64_e32 v[82:83], v[102:103]
	v_mov_b64_e32 v[84:85], v[104:105]
	v_mov_b64_e32 v[78:79], v[106:107]
	v_mov_b64_e32 v[80:81], v[108:109]
	v_lshlrev_b32_e32 v86, 16, v70
	v_and_b32_e32 v87, 0xffff0000, v70
	v_lshlrev_b32_e32 v70, 16, v71
	v_and_b32_e32 v71, 0xffff0000, v71
	v_lshlrev_b32_e32 v88, 16, v82
	v_and_b32_e32 v89, 0xffff0000, v82
	v_lshlrev_b32_e32 v82, 16, v83
	v_and_b32_e32 v83, 0xffff0000, v83
	v_pk_add_f32 v[86:87], v[86:87], 0 op_sel_hi:[1,0]
	v_pk_add_f32 v[70:71], v[70:71], 0 op_sel_hi:[1,0]
	v_lshlrev_b32_e32 v90, 16, v84
	v_and_b32_e32 v91, 0xffff0000, v84
	v_lshlrev_b32_e32 v84, 16, v85
	v_and_b32_e32 v85, 0xffff0000, v85
	v_pk_add_f32 v[86:87], v[86:87], v[88:89]
	v_pk_add_f32 v[70:71], v[70:71], v[82:83]
	v_pk_add_f32 v[82:83], v[86:87], v[90:91]
	v_pk_add_f32 v[70:71], v[70:71], v[84:85]
	v_pk_fma_f32 v[24:25], v[78:79], v[82:83], v[24:25]
	v_pk_fma_f32 v[26:27], v[80:81], v[70:71], v[26:27]
	global_store_dwordx4 v[62:63], v[24:27], off offset:1024
	v_mov_b64_e32 v[70:71], v[110:111]
	v_mov_b64_e32 v[82:83], v[112:113]
	v_mov_b64_e32 v[84:85], v[114:115]
	v_mov_b64_e32 v[78:79], v[116:117]
	v_mov_b64_e32 v[80:81], v[118:119]
	v_lshlrev_b32_e32 v86, 16, v70
	v_and_b32_e32 v87, 0xffff0000, v70
	v_lshlrev_b32_e32 v70, 16, v71
	v_and_b32_e32 v71, 0xffff0000, v71
	v_lshlrev_b32_e32 v88, 16, v82
	v_and_b32_e32 v89, 0xffff0000, v82
	v_lshlrev_b32_e32 v82, 16, v83
	v_and_b32_e32 v83, 0xffff0000, v83
	v_pk_add_f32 v[86:87], v[86:87], 0 op_sel_hi:[1,0]
	v_pk_add_f32 v[70:71], v[70:71], 0 op_sel_hi:[1,0]
	v_lshlrev_b32_e32 v90, 16, v84
	v_and_b32_e32 v91, 0xffff0000, v84
	v_lshlrev_b32_e32 v84, 16, v85
	v_and_b32_e32 v85, 0xffff0000, v85
	v_pk_add_f32 v[86:87], v[86:87], v[88:89]
	v_pk_add_f32 v[70:71], v[70:71], v[82:83]
	v_pk_add_f32 v[82:83], v[86:87], v[90:91]
	v_pk_add_f32 v[70:71], v[70:71], v[84:85]
	v_pk_fma_f32 v[20:21], v[78:79], v[82:83], v[20:21]
	v_pk_fma_f32 v[22:23], v[80:81], v[70:71], v[22:23]
	global_store_dwordx4 v[62:63], v[20:23], off offset:2048
	v_mov_b64_e32 v[70:71], v[120:121]
	v_mov_b64_e32 v[78:79], v[122:123]
	v_mov_b64_e32 v[68:69], v[124:125]
	v_mov_b64_e32 v[64:65], v[126:127]
	v_mov_b64_e32 v[66:67], v[128:129]
	v_lshlrev_b32_e32 v80, 16, v70
	v_and_b32_e32 v81, 0xffff0000, v70
	v_lshlrev_b32_e32 v70, 16, v71
	v_and_b32_e32 v71, 0xffff0000, v71
	v_lshlrev_b32_e32 v82, 16, v78
	v_and_b32_e32 v83, 0xffff0000, v78
	v_lshlrev_b32_e32 v78, 16, v79
	v_and_b32_e32 v79, 0xffff0000, v79
	v_pk_add_f32 v[80:81], v[80:81], 0 op_sel_hi:[1,0]
	v_pk_add_f32 v[70:71], v[70:71], 0 op_sel_hi:[1,0]
	v_lshlrev_b32_e32 v84, 16, v68
	v_and_b32_e32 v85, 0xffff0000, v68
	v_lshlrev_b32_e32 v68, 16, v69
	v_and_b32_e32 v69, 0xffff0000, v69
	v_pk_add_f32 v[80:81], v[80:81], v[82:83]
	v_pk_add_f32 v[70:71], v[70:71], v[78:79]
	v_pk_add_f32 v[78:79], v[80:81], v[84:85]
	v_pk_add_f32 v[68:69], v[70:71], v[68:69]
	v_pk_fma_f32 v[16:17], v[64:65], v[78:79], v[16:17]
	v_pk_fma_f32 v[18:19], v[66:67], v[68:69], v[18:19]
	global_store_dwordx4 v[62:63], v[16:19], off offset:3072

.LBB0_439:
	s_or_b64 exec, exec, s[16:17]
	v_cmp_lt_i32_e32 vcc, s28, v62
	s_and_b64 s[24:25], s[12:13], vcc
	s_and_saveexec_b64 s[16:17], s[24:25]
	s_cbranch_execz .LBB0_441
	v_lshlrev_b64 v[64:65], 11, v[184:185]
	v_lshl_add_u64 v[66:67], v[44:45], 0, v[64:65]
	v_add_co_u32_e32 v68, vcc, 0x800000, v66
	global_load_dwordx2 v[82:83], v[66:67], off
	s_nop 0
	v_addc_co_u32_e32 v69, vcc, 0, v67, vcc
	global_load_dwordx2 v[84:85], v[68:69], off
	v_add_co_u32_e32 v70, vcc, 0x1000000, v66
	v_lshlrev_b64 v[64:65], 12, v[184:185]
	s_nop 0
	v_addc_co_u32_e32 v71, vcc, 0, v67, vcc
	global_load_dwordx2 v[86:87], v[70:71], off
	global_load_dwordx4 v[78:81], v[34:35], off
	global_load_dwordx2 v[100:101], v[66:67], off offset:512
	global_load_dwordx2 v[102:103], v[68:69], off offset:512
	global_load_dwordx2 v[104:105], v[70:71], off offset:512
	global_load_dwordx4 v[106:109], v[36:37], off
	global_load_dwordx2 v[110:111], v[66:67], off offset:1024
	global_load_dwordx2 v[112:113], v[68:69], off offset:1024
	global_load_dwordx2 v[114:115], v[70:71], off offset:1024
	global_load_dwordx4 v[116:119], v[38:39], off
	global_load_dwordx2 v[120:121], v[66:67], off offset:1536
	global_load_dwordx2 v[122:123], v[68:69], off offset:1536
	global_load_dwordx2 v[124:125], v[70:71], off offset:1536
	global_load_dwordx4 v[126:129], v[40:41], off
	v_lshl_add_u64 v[64:65], v[46:47], 0, v[64:65]
	s_waitcnt vmcnt(0)
	v_lshlrev_b32_e32 v88, 16, v82
	v_and_b32_e32 v89, 0xffff0000, v82
	v_lshlrev_b32_e32 v82, 16, v83
	v_and_b32_e32 v83, 0xffff0000, v83
	v_pk_add_f32 v[88:89], v[88:89], 0 op_sel_hi:[1,0]
	v_pk_add_f32 v[82:83], v[82:83], 0 op_sel_hi:[1,0]
	v_lshlrev_b32_e32 v90, 16, v84
	v_and_b32_e32 v91, 0xffff0000, v84
	v_lshlrev_b32_e32 v84, 16, v85
	v_and_b32_e32 v85, 0xffff0000, v85
	v_pk_add_f32 v[88:89], v[88:89], v[90:91]
	v_lshlrev_b32_e32 v90, 16, v86
	v_and_b32_e32 v91, 0xffff0000, v86
	v_pk_add_f32 v[82:83], v[82:83], v[84:85]
	v_lshlrev_b32_e32 v84, 16, v87
	v_and_b32_e32 v85, 0xffff0000, v87
	v_pk_add_f32 v[86:87], v[88:89], v[90:91]
	v_pk_add_f32 v[82:83], v[82:83], v[84:85]
	v_pk_fma_f32 v[0:1], v[78:79], v[86:87], v[0:1]
	v_pk_fma_f32 v[2:3], v[80:81], v[82:83], v[2:3]
	global_store_dwordx4 v[64:65], v[0:3], off
	v_mov_b64_e32 v[82:83], v[100:101]
	v_mov_b64_e32 v[84:85], v[102:103]
	v_mov_b64_e32 v[86:87], v[104:105]
	v_mov_b64_e32 v[78:79], v[106:107]
	v_mov_b64_e32 v[80:81], v[108:109]
	v_lshlrev_b32_e32 v88, 16, v82
	v_and_b32_e32 v89, 0xffff0000, v82
	v_lshlrev_b32_e32 v82, 16, v83
	v_and_b32_e32 v83, 0xffff0000, v83
	v_lshlrev_b32_e32 v90, 16, v84
	v_and_b32_e32 v91, 0xffff0000, v84
	v_lshlrev_b32_e32 v84, 16, v85
	v_and_b32_e32 v85, 0xffff0000, v85
	v_pk_add_f32 v[88:89], v[88:89], 0 op_sel_hi:[1,0]
	v_pk_add_f32 v[82:83], v[82:83], 0 op_sel_hi:[1,0]
	v_lshlrev_b32_e32 v92, 16, v86
	v_and_b32_e32 v93, 0xffff0000, v86
	v_lshlrev_b32_e32 v86, 16, v87
	v_and_b32_e32 v87, 0xffff0000, v87
	v_pk_add_f32 v[88:89], v[88:89], v[90:91]
	v_pk_add_f32 v[82:83], v[82:83], v[84:85]
	v_pk_add_f32 v[84:85], v[88:89], v[92:93]
	v_pk_add_f32 v[82:83], v[82:83], v[86:87]
	v_pk_fma_f32 v[4:5], v[78:79], v[84:85], v[4:5]
	v_pk_fma_f32 v[6:7], v[80:81], v[82:83], v[6:7]
	global_store_dwordx4 v[64:65], v[4:7], off offset:1024
	v_mov_b64_e32 v[82:83], v[110:111]
	v_mov_b64_e32 v[84:85], v[112:113]
	v_mov_b64_e32 v[86:87], v[114:115]
	v_mov_b64_e32 v[78:79], v[116:117]
	v_mov_b64_e32 v[80:81], v[118:119]
	v_lshlrev_b32_e32 v88, 16, v82
	v_and_b32_e32 v89, 0xffff0000, v82
	v_lshlrev_b32_e32 v82, 16, v83
	v_and_b32_e32 v83, 0xffff0000, v83
	v_lshlrev_b32_e32 v90, 16, v84
	v_and_b32_e32 v91, 0xffff0000, v84
	v_lshlrev_b32_e32 v84, 16, v85
	v_and_b32_e32 v85, 0xffff0000, v85
	v_pk_add_f32 v[88:89], v[88:89], 0 op_sel_hi:[1,0]
	v_pk_add_f32 v[82:83], v[82:83], 0 op_sel_hi:[1,0]
	v_lshlrev_b32_e32 v92, 16, v86
	v_and_b32_e32 v93, 0xffff0000, v86
	v_lshlrev_b32_e32 v86, 16, v87
	v_and_b32_e32 v87, 0xffff0000, v87
	v_pk_add_f32 v[88:89], v[88:89], v[90:91]
	v_pk_add_f32 v[82:83], v[82:83], v[84:85]
	v_pk_add_f32 v[84:85], v[88:89], v[92:93]
	v_pk_add_f32 v[82:83], v[82:83], v[86:87]
	v_pk_fma_f32 v[8:9], v[78:79], v[84:85], v[8:9]
	v_pk_fma_f32 v[10:11], v[80:81], v[82:83], v[10:11]
	global_store_dwordx4 v[64:65], v[8:11], off offset:2048
	v_mov_b64_e32 v[78:79], v[120:121]
	v_mov_b64_e32 v[80:81], v[122:123]
	v_mov_b64_e32 v[70:71], v[124:125]
	v_mov_b64_e32 v[66:67], v[126:127]
	v_mov_b64_e32 v[68:69], v[128:129]
	v_lshlrev_b32_e32 v82, 16, v78
	v_and_b32_e32 v83, 0xffff0000, v78
	v_lshlrev_b32_e32 v78, 16, v79
	v_and_b32_e32 v79, 0xffff0000, v79
	v_lshlrev_b32_e32 v84, 16, v80
	v_and_b32_e32 v85, 0xffff0000, v80
	v_lshlrev_b32_e32 v80, 16, v81
	v_and_b32_e32 v81, 0xffff0000, v81
	v_pk_add_f32 v[82:83], v[82:83], 0 op_sel_hi:[1,0]
	v_pk_add_f32 v[78:79], v[78:79], 0 op_sel_hi:[1,0]
	v_lshlrev_b32_e32 v86, 16, v70
	v_and_b32_e32 v87, 0xffff0000, v70
	v_lshlrev_b32_e32 v70, 16, v71
	v_and_b32_e32 v71, 0xffff0000, v71
	v_pk_add_f32 v[82:83], v[82:83], v[84:85]
	v_pk_add_f32 v[78:79], v[78:79], v[80:81]
	v_pk_add_f32 v[80:81], v[82:83], v[86:87]
	v_pk_add_f32 v[70:71], v[78:79], v[70:71]
	v_pk_fma_f32 v[12:13], v[66:67], v[80:81], v[12:13]
	v_pk_fma_f32 v[14:15], v[68:69], v[70:71], v[14:15]
	global_store_dwordx4 v[64:65], v[12:15], off offset:3072
